# in-proj: WGs j>=16 of each XCD start ~9us late so the two halves' epilogue store bursts do not coincide
# baseline (speedup 1.0000x reference)
;     __host__ __device__ void init(int N_, int G_, int c_) { nN = N_ / BM; mn.init(NPROMPT, N_, G_, c_); G = G_; c = c_; }
; __global__ void __launch_bounds__(NWAVES * 64, 2) fwd(Args args_unused) {
;     ...
;         if (IN(pb + 2)) {
;             PH_PTRS PH_LAYER
;             pg8::Gemm g{XB, (const bf16*)(wl + WL_IN), M, NZT, DM, DM, DM, 0}; pg8::StaticOrder S; S.init(M, NZT, G, bx);
;             pg8::EpiZ E{Z, SSQ, (const float*)(ws + WS_SHW2) + (size_t)l * NSEQ * NZT, out, DT, A->in[I_DTB] + l * 16, l};
;             pg8::gemm_phase<pg8::EpiZ, pg8::StaticOrder>(lds, g, S, E);
.LBB0_637:
	v_readlane_b32 s98, v254, 3
	s_nop 3
	s_lshr_b32 s98, s98, 4
	s_and_b32 s98, s98, 1
	s_mul_i32 s98, s98, 9
	s_cmp_eq_u32 s98, 0
	s_cbranch_scc1 .Lstag_done_0
.Lstag_loop_0:
	s_sleep 32
	s_sub_u32 s98, s98, 1
	s_cmp_lg_u32 s98, 0
	s_cbranch_scc1 .Lstag_loop_0
